# diff jobs enumerated in 4 groups of 8 (batch,head) pairs so that jobs sharing K/V run concurrently (L2 reuse); same jobs, bijective reorder
# speedup vs baseline: 1.0081x; 1.0029x over previous
; DI void sb_job(const Params& p, int b, int head, int qb, unsigned char* smem) {
;   int tid_ = threadIdx.x & 255; asm volatile("" : "+v"(tid_));
;   const int tid = tid_, lane = tid & 63, wave = tid >> 6, h = lane >> 5, lq = lane & 31;
;   const int t0 = qb * 128, tw0 = t0 + 32 * wave, tq = tw0 + lq;
;   bf16x8 qf[4];
;   {
;     const u16* qr = p.qsb + (size_t)(b * TP + tq) * 256 + head * 64 + 8 * h;
; #pragma unroll
;     for (int s = 0; s < 4; ++s) qf[s] = *(const bf16x8*)(qr + 16 * s);
;   }
;   f32x16 O[2] = {zero16(), zero16()};
;   float carry = 0.f;
;   const u16* Kp = p.ksb + (size_t)b * TP * 256 + head * 64;
;   const u16* VT = p.vtsb + (size_t)(b * 256 + head * 64) * TP;
;   const int ntile = 2 * (qb + 1);
;   u32x4 rk[2], rv[2];
;   ld_tile_g<2>(rk, Kp, 256, (ntile - 1) * 64, false, tid); ld_tile_g<2>(rv, VT, TP, (ntile - 1) * 64, true, tid);
;   st_tile_s<2>(rk, smem, true, tid); st_tile_s<2>(rv, smem + 9216, false, tid);
;   __syncthreads();
; DI void phase_attn(const Params& p, int layer, int phase, unsigned char* smem) {
;     ...
;     const int jp = next_job(ctr, smem);
;     if (jp >= 2640) break;
;     if (jp < 1056) { const int qb = 32 - jp / 32, r = jp & 31; diff_job8(p, layer, r >> 2, r & 3, qb, smem); continue; }
;     int half = threadIdx.x >> 8; asm volatile("" : "+v"(half));
;     unsigned char* sm = smem + half * HALF_BYTES;
;     const int job = 2 * (jp - 1056) + half;
;     if (job < 2112) { idx_job(p, job & 7, 263 - (job >> 3), sm); }
;     else { const int i = job - 2112; const int qb = 32 - i / 32, r = i & 31; sb_job(p, r >> 2, r & 3, qb, sm); }
.LBB0_364:
	s_or_b64 exec, exec, s[2:3]
	s_waitcnt lgkmcnt(0)
	s_barrier
	ds_read_b32 v0, v200
	s_movk_i32 s2, 0xa4f
	s_waitcnt lgkmcnt(0)
	v_mul_u32_u24_e32 v2, 0xf84, v0
	v_lshrrev_b32_e32 v2, 20, v2
	v_mul_u32_u24_e32 v255, 0x108, v2
	v_sub_u32_e32 v255, v0, v255
	v_and_b32_e32 v254, 7, v255
	v_lshl_add_u32 v254, v2, 3, v254
	v_lshrrev_b32_e32 v255, 3, v255
	v_lshl_add_u32 v254, v255, 5, v254
	v_cmp_gt_u32_e32 vcc, 0x420, v0
	s_nop 1
	v_cndmask_b32_e32 v0, v0, v254, vcc
	s_nop 1
	v_cmp_lt_i32_e32 vcc, s2, v0
	v_readfirstlane_b32 s10, v0
	s_mov_b64 s[2:3], -1
	s_cbranch_vccnz .LBB0_359
	s_cmpk_gt_i32 s10, 0x41f
	s_cbranch_scc0 .LBB0_913
	v_mov_b32_e32 v0, v167
	s_mov_b32 s2, 0x12800
	s_waitcnt vmcnt(8)
	v_mul_lo_u32 v96, v0, s2
	s_lshl_b32 s2, s10, 1
	s_addk_i32 s2, 0xf7c0
	v_add_u32_e32 v0, s2, v0
	s_movk_i32 s2, 0x83f
	v_cmp_lt_i32_e32 vcc, s2, v0
	s_and_saveexec_b64 s[2:3], vcc
	s_xor_b64 s[2:3], exec, s[2:3]
	s_cbranch_execz .LBB0_388
	v_add_u32_e32 v2, 0xfffff7c0, v0
	v_mov_b32_e32 v15, v196
	v_lshrrev_b32_e32 v14, 5, v2
	v_sub_u32_e32 v10, 32, v14
	v_ashrrev_i32_e32 v2, 1, v15
	v_and_b32_e32 v2, 0xffffffe0, v2
	v_and_b32_e32 v16, 31, v15
	v_lshl_add_u32 v97, v10, 7, v2
	s_load_dwordx16 s[56:71], s[0:1], 0xc8
	v_bfe_u32 v8, v0, 2, 3
	v_or_b32_e32 v99, v97, v16
	s_movk_i32 s6, 0x1080
	v_mad_u32_u24 v2, v8, s6, v99
	v_ashrrev_i32_e32 v3, 31, v2
	v_mul_u32_u24_e32 v6, 0x108000, v8
	v_lshlrev_b64 v[4:5], 9, v[2:3]
	v_lshlrev_b32_e32 v0, 6, v0
	v_lshlrev_b32_e32 v6, 1, v6
	v_mov_b32_e32 v7, v1
	s_waitcnt lgkmcnt(0)
	v_lshl_add_u64 v[4:5], s[64:65], 0, v[4:5]
	v_and_b32_e32 v98, 0xc0, v0
	v_lshl_add_u64 v[6:7], s[66:67], 0, v[6:7]
	s_load_dwordx16 s[56:71], s[0:1], 0x108
	v_lshlrev_b32_e32 v0, 1, v98
	v_lshl_add_u64 v[4:5], v[4:5], 0, v[0:1]
	v_lshl_add_u64 v[6:7], v[6:7], 0, v[0:1]
	v_lshl_or_b32 v0, v8, 8, v98
	v_mul_u32_u24_e32 v0, 0x1080, v0
	v_lshlrev_b32_e32 v0, 1, v0
	v_lshlrev_b32_e32 v17, 1, v10
	s_waitcnt lgkmcnt(0)
	v_lshl_add_u64 v[8:9], s[60:61], 0, v[0:1]
	v_or_b32_e32 v107, 1, v17
	v_lshlrev_b32_e32 v0, 4, v15
	v_lshlrev_b32_e32 v10, 6, v107
	v_and_b32_e32 v0, 0x70, v0
	v_ashrrev_i32_e32 v112, 3, v15
	v_add_u32_e32 v12, 0x100, v15
	v_lshl_add_u64 v[100:101], v[6:7], 0, v[0:1]
	v_add_u32_e32 v6, v112, v10
	v_ashrrev_i32_e32 v113, 3, v12
	v_ashrrev_i32_e32 v7, 31, v6
	v_add_u32_e32 v12, v113, v10
	v_lshlrev_b64 v[6:7], 9, v[6:7]
	v_ashrrev_i32_e32 v13, 31, v12
	v_ashrrev_i32_e32 v11, 31, v10
	v_lshl_add_u64 v[6:7], v[100:101], 0, v[6:7]
	v_lshlrev_b64 v[12:13], 9, v[12:13]
	v_lshl_add_u64 v[12:13], v[100:101], 0, v[12:13]
	global_load_dwordx4 v[64:67], v[6:7], off
	global_load_dwordx4 v[76:79], v[12:13], off
	v_lshl_add_u64 v[6:7], v[10:11], 1, v[8:9]
	v_lshl_add_u64 v[6:7], v[6:7], 0, v[0:1]
	v_mad_i64_i32 v[102:103], s[4:5], v112, s6, 0
	v_lshl_add_u64 v[10:11], v[102:103], 1, v[6:7]
	v_mad_i64_i32 v[104:105], s[4:5], v113, s6, 0
	v_lshl_add_u64 v[6:7], v[104:105], 1, v[6:7]
	global_load_dwordx4 v[88:91], v[10:11], off
	global_load_dwordx4 v[92:95], v[6:7], off
	v_bfe_u32 v10, v15, 5, 1
	v_lshlrev_b32_e32 v6, 4, v10
	v_mov_b32_e32 v7, v1
	v_lshl_add_u64 v[4:5], v[4:5], 0, v[6:7]
	global_load_dwordx4 v[68:71], v[4:5], off
	global_load_dwordx4 v[72:75], v[4:5], off offset:32
	global_load_dwordx4 v[80:83], v[4:5], off offset:64
	global_load_dwordx4 v[84:87], v[4:5], off offset:96
	v_lshlrev_b32_e32 v5, 1, v112
	v_lshrrev_b32_e32 v7, 1, v112
	v_and_b32_e32 v4, 0xffffff3, v112
	v_and_b32_e32 v5, 8, v5
	v_and_b32_e32 v7, 4, v7
	v_lshlrev_b32_e32 v12, 1, v113
	v_lshrrev_b32_e32 v13, 1, v113
	v_and_b32_e32 v11, 0xffffff3, v113
	v_or3_b32 v4, v5, v4, v7
	v_and_b32_e32 v5, 8, v12
	v_and_b32_e32 v7, 4, v13
	v_mul_lo_u32 v117, v4, s78
	v_or3_b32 v4, v5, v11, v7
	v_add_u32_e32 v119, v96, v0
	v_lshl_add_u64 v[110:111], v[8:9], 0, v[0:1]
	v_mul_u32_u24_e32 v0, 0x90, v16
	v_mul_lo_u32 v114, v112, s78
	v_mul_lo_u32 v116, v113, s78
	v_mul_lo_u32 v118, v4, s78
	v_add3_u32 v0, v96, v0, v6
	v_lshlrev_b32_e32 v106, 3, v10
	v_lshlrev_b64 v[108:109], 8, v[2:3]
	v_add_u32_e32 v2, v119, v117
	v_add_u32_e32 v3, v119, v118
	v_add_u32_e32 v4, v119, v114
	v_add_u32_e32 v5, v119, v116
	v_add_u32_e32 v96, 0x1200, v0
	v_add_u32_e32 v121, 0x2440, v0
	v_lshlrev_b32_e32 v0, 7, v14
	v_mov_b32_e32 v14, v1
	v_mov_b32_e32 v15, v1
	v_add_u32_e32 v115, 2, v17
	v_cmp_eq_u32_e64 s[40:41], 0, v10
	v_sub_u32_e32 v122, 0, v0
	v_sub_u32_e32 v123, v106, v0
	v_mov_b32_e32 v0, v1
	v_mov_b32_e32 v6, v1
	v_mov_b32_e32 v7, v1
	s_waitcnt vmcnt(7)
	ds_write_b128 v2, v[64:67]
	s_waitcnt vmcnt(6)
	ds_write_b128 v3, v[76:79]
	s_waitcnt vmcnt(5)
	ds_write_b128 v4, v[88:91] offset:9216
	s_waitcnt vmcnt(4)
	ds_write_b128 v5, v[92:95] offset:9216
	v_mov_b32_e32 v2, v1
	v_mov_b32_e32 v3, v1
	v_mov_b32_e32 v4, v1
	v_mov_b32_e32 v5, v1
	v_mov_b32_e32 v8, v1
	v_mov_b32_e32 v9, v1
	v_mov_b32_e32 v10, v1
	v_mov_b32_e32 v11, v1
	v_mov_b32_e32 v12, v1
	v_mov_b32_e32 v13, v1
	v_mov_b64_e32 v[30:31], v[14:15]
	v_mov_b64_e32 v[46:47], v[14:15]
	s_mov_b32 s6, 0
	v_max_i32_e32 v120, 0, v115
	v_mov_b32_e32 v124, 0
	s_mov_b64 s[8:9], 0
	v_mov_b64_e32 v[28:29], v[12:13]
	v_mov_b64_e32 v[26:27], v[10:11]
	v_mov_b64_e32 v[24:25], v[8:9]
	v_mov_b64_e32 v[22:23], v[6:7]
	v_mov_b64_e32 v[20:21], v[4:5]
	v_mov_b64_e32 v[18:19], v[2:3]
	v_mov_b64_e32 v[16:17], v[0:1]
	v_mov_b64_e32 v[44:45], v[12:13]
	v_mov_b64_e32 v[42:43], v[10:11]
	v_mov_b64_e32 v[40:41], v[8:9]
	v_mov_b64_e32 v[38:39], v[6:7]
	v_mov_b64_e32 v[36:37], v[4:5]
	v_mov_b64_e32 v[34:35], v[2:3]
	v_mov_b64_e32 v[32:33], v[0:1]
	s_waitcnt lgkmcnt(0)
	s_barrier
	s_branch .LBB0_371
